# helper priority + hoisted compute setup + compute waves skip the y flush (helpers flush both halves) + coalesced waits
# speedup vs baseline: 1.0273x; 1.0002x over previous
.Lmy_f_hlp:
	s_setprio 3
	s_cmp_eq_u32 s65, 0
	s_cbranch_scc1 .Lmy_f_nofl
	v_subrev_u32_e32 v70, 16, v70
	v_add_u32_e32 v71, 16, v71
	s_and_b32 s96, s64, 0x800
	v_lshl_add_u32 v21, s96, 2, v68
	v_add_u32_e32 v21, 0xfffff000, v21
	v_cndmask_b32_e64 v76, v71, v70, s[4:5]
	ds_read_b128 v[72:75], v21
	v_ashrrev_i32_e32 v77, 31, v76
	v_lshl_add_u64 v[76:77], v[76:77], 0, s[40:41]
	v_lshlrev_b64 v[76:77], 12, v[76:77]
	v_lshl_add_u64 v[76:77], v[54:55], 0, v[76:77]
	s_waitcnt lgkmcnt(0)
	global_store_dwordx4 v[76:77], v[72:75], off
	v_add_u32_e32 v70, 16, v70
	v_subrev_u32_e32 v71, 16, v71

.Lmy_ck_drE_h:
	s_waitcnt lgkmcnt(0)
	s_bfe_u32 s96, s62, 0x20006
	s_and_b32 s97, s96, 1
	s_mul_i32 s97, s97, 0x2700
	s_mov_b32 s101, 0x1c000
	s_mov_b32 s100, 0x6100
	s_bitcmp0_b32 s65, 0
	s_cselect_b32 s101, 0xe000, s101
	s_cselect_b32 s100, 0x4e00, s100
	s_cmp_gt_u32 s96, 1
	s_cselect_b32 s100, s100, 0
	s_add_i32 s97, s97, s101
	s_add_i32 s97, s97, s100
	s_mov_b32 s96, s97
	v_and_b32_e32 v72, 3, v233
	v_lshrrev_b32_e32 v73, 2, v233
	v_lshlrev_b32_e32 v72, 2, v72
	v_lshl_add_u32 v72, v73, 8, v72
	v_lshl_add_u32 v72, v234, 6, v72
	s_add_i32 s97, s96, 0x1000
	v_add_u32_e32 v78, s97, v72
	v_xor_b32_e32 v79, v224, v234
	v_lshl_add_u32 v79, v79, 4, s96
	ds_read_b128 v[96:99], v79
	ds_read_b128 v[100:103], v79 offset:1024
	ds_read_b128 v[104:107], v79 offset:2048
	ds_read_b128 v[108:111], v79 offset:3072
	ds_read_b32 v80, v78
	ds_read_b32 v81, v78 offset:16
	ds_read_b32 v82, v78 offset:32
	ds_read_b32 v83, v78 offset:48
	ds_read_b32 v84, v78 offset:1024
	ds_read_b32 v85, v78 offset:1040
	ds_read_b32 v86, v78 offset:1056
	ds_read_b32 v87, v78 offset:1072
	ds_read_b32 v88, v78 offset:2048
	ds_read_b32 v89, v78 offset:2064
	ds_read_b32 v90, v78 offset:2080
	ds_read_b32 v91, v78 offset:2096
	ds_read_b32 v92, v78 offset:3072
	ds_read_b32 v93, v78 offset:3088
	ds_read_b32 v94, v78 offset:3104
	ds_read_b32 v95, v78 offset:3120
	v_lshl_add_u32 v74, v224, 2, s96
	ds_write_b32 v74, v235 offset:9728
	v_add_u32_e32 v75, -1, v233
	v_mov_b32_e32 v76, -1
	v_cndmask_b32_e64 v75, v76, v75, s[98:99]
	v_cmp_lt_u32_e64 s[100:101], 7, v233
	v_add_u32_e32 v76, -8, v233
	v_and_b32_e32 v77, 1, v234
	v_cndmask_b32_e64 v75, v75, v76, s[100:101]
	v_lshlrev_b32_e32 v77, 2, v77
	v_sub_u32_e32 v76, v75, v77
	v_lshlrev_b32_e32 v77, 2, v234
	v_sub_u32_e32 v77, v233, v77
	v_add_u32_e32 v77, -1, v77
	s_waitcnt lgkmcnt(10)
	v_mfma_f32_16x16x4_f32 v[244:247], v80, v96, 0
	v_mfma_f32_16x16x4_f32 v[240:243], v81, v97, 0
	v_mfma_f32_16x16x4_f32 v[244:247], v82, v98, v[244:247]
	v_mfma_f32_16x16x4_f32 v[240:243], v83, v99, v[240:243]
	v_mfma_f32_16x16x4_f32 v[244:247], v84, v100, v[244:247]
	v_mfma_f32_16x16x4_f32 v[240:243], v85, v101, v[240:243]
	v_mfma_f32_16x16x4_f32 v[244:247], v86, v102, v[244:247]
	s_waitcnt lgkmcnt(2)
	v_mfma_f32_16x16x4_f32 v[240:243], v87, v103, v[240:243]
	v_mfma_f32_16x16x4_f32 v[244:247], v88, v104, v[244:247]
	v_mfma_f32_16x16x4_f32 v[240:243], v89, v105, v[240:243]
	v_mfma_f32_16x16x4_f32 v[244:247], v90, v106, v[244:247]
	v_mfma_f32_16x16x4_f32 v[240:243], v91, v107, v[240:243]
	v_mfma_f32_16x16x4_f32 v[244:247], v92, v108, v[244:247]
	v_mfma_f32_16x16x4_f32 v[240:243], v93, v109, v[240:243]
	v_mfma_f32_16x16x4_f32 v[244:247], v94, v110, v[244:247]
	s_waitcnt lgkmcnt(1)
	v_mfma_f32_16x16x4_f32 v[240:243], v95, v111, v[240:243]
	s_nop 9
	v_add_f32_e32 v244, v244, v240
	v_add_f32_e32 v245, v245, v241
	v_add_f32_e32 v246, v246, v242
	v_add_f32_e32 v247, v247, v243
	v_cmp_le_i32_e64 s[96:97], 0, v76
	v_cmp_le_i32_e64 s[100:101], 1, v76
	s_nop 0
	v_cndmask_b32_e64 v128, 0, v244, s[96:97]
	v_cndmask_b32_e64 v129, 0, v245, s[100:101]
	v_cmp_le_i32_e64 s[96:97], 2, v76
	v_cmp_le_i32_e64 s[100:101], 3, v76
	s_nop 0
	v_cndmask_b32_e64 v130, 0, v246, s[96:97]
	v_cndmask_b32_e64 v131, 0, v247, s[100:101]
	s_bfe_u32 s96, s62, 0x20006
	s_and_b32 s97, s96, 1
	s_mul_i32 s97, s97, 0x2700
	s_mov_b32 s101, 0x1c000
	s_mov_b32 s100, 0x6100
	s_bitcmp0_b32 s65, 0
	s_cselect_b32 s101, 0xe000, s101
	s_cselect_b32 s100, 0x4e00, s100
	s_cmp_gt_u32 s96, 1
	s_cselect_b32 s100, s100, 0
	s_add_i32 s97, s97, s101
	s_add_i32 s97, s97, s100
	v_xor_b32_e32 v74, v224, v234
	v_lshl_add_u32 v74, v74, 4, s97
	ds_write_b128 v74, v[128:131] offset:8448
	v_lshlrev_b32_e32 v75, 7, v234
	v_lshl_add_u32 v75, v233, 2, v75
	v_add_u32_e32 v75, s97, v75
	v_cmp_le_i32_e64 s[96:97], 0, v77
	v_cmp_le_i32_e64 s[100:101], 1, v77
	s_nop 0
	v_cndmask_b32_e64 v132, 0, v244, s[96:97]
	v_cndmask_b32_e64 v133, 0, v245, s[100:101]
	v_cmp_le_i32_e64 s[96:97], 2, v77
	v_cmp_le_i32_e64 s[100:101], 3, v77
	s_nop 0
	v_cndmask_b32_e64 v134, 0, v246, s[96:97]
	v_cndmask_b32_e64 v135, 0, v247, s[100:101]
	s_mov_b64 exec, 0x00ff00ff
	ds_write_b32 v75, v132 offset:9472
	ds_write_b32 v75, v133 offset:9504
	ds_write_b32 v75, v134 offset:9536
	ds_write_b32 v75, v135 offset:9568
	s_mov_b64 exec, -1
	s_setprio 0
	s_branch .LBB0_655
	s_nop 0
	s_nop 0
	s_nop 0
	s_nop 0
	s_nop 0
	s_nop 0
	s_nop 0
	s_nop 0
	s_nop 0
	s_nop 0
	s_nop 0
	s_nop 0
	s_nop 0
	s_nop 0
	s_nop 0
	s_nop 0
	s_nop 0
	s_nop 0
	s_nop 0
	s_nop 0
	s_nop 0
	s_nop 0
	s_nop 0
	s_nop 0
	s_nop 0
	s_nop 0
	s_nop 0
	s_nop 0
	s_nop 0
	s_nop 0
	s_nop 0
	s_nop 0
	s_nop 0
	s_nop 0
	s_nop 0
	s_nop 0
	s_nop 0
	s_nop 0
	s_nop 0
	s_nop 0
	s_nop 0
	s_nop 0
	s_nop 0
	s_nop 0
	s_nop 0
	s_nop 0
	s_nop 0
	s_nop 0
	s_nop 0
